# S5 scans: re and im of a state now share a lane (separate accumulators), the recurrence uses plain FMAs only (no DPP operand)
# baseline (speedup 1.0000x reference)
.Lp6_fwd:
	v_lshlrev_b32_e32 v4, 11, v3
	v_lshl_add_u32 v4, v1, 4, v4
	v_lshlrev_b32_e32 v5, 6, v0
	v_lshl_add_u32 v5, v1, 4, v5
	v_lshlrev_b32_e32 v6, 3, v0
	v_mov_b32_e32 v9, 0x420000
	v_mul_lo_u32 v7, v1, v9
	v_lshl_add_u32 v7, v0, 3, v7
	v_and_b32_e32 v9, 1, v0
	v_mov_b32_e32 v10, 0x80000000
	v_cmp_eq_u32_e32 vcc, 0, v9
	s_nop 3
	v_cndmask_b32_e32 v8, 0, v10, vcc
	s_mov_b32 s27, -1
	s_mov_b32 s5, s8
	s_mov_b32 s35, 1
	s_branch .Lp6_prefetch
.Lp6_top:
	s_waitcnt vmcnt(2)
.Lp6_top_body:
	v_mov_b64_e32 v[52:53], v[68:69]
	v_mov_b64_e32 v[54:55], v[70:71]
	v_mov_b64_e32 v[56:57], v[72:73]
	v_mov_b64_e32 v[58:59], v[74:75]
	v_mov_b64_e32 v[60:61], v[76:77]
	v_mov_b64_e32 v[62:63], v[78:79]
	v_mov_b64_e32 v[64:65], v[80:81]
	v_mov_b64_e32 v[66:67], v[82:83]
	s_mov_b32 s4, s5
	s_add_i32 s5, s5, s9
	s_cmpk_gt_u32 s5, 0x83f
	s_cbranch_scc1 .Lp6_compute

.Lp6_compute:
	s_lshr_b32 s6, s4, 4
	s_and_b32 s7, s4, 15
	s_cmp_eq_u32 s7, s27
	s_cbranch_scc1 .Lp6_have_g
	s_mov_b32 s27, s7
	s_lshl_b32 s25, s7, 2
	s_add_i32 s25, s25, s20
	s_lshl_b32 s10, s25, 1
	s_add_i32 s10, s10, s22
	s_lshl_b32 s10, s10, 12
	s_add_u32 s46, s14, s10
	s_addc_u32 s47, s15, 0
	s_lshl_b32 s10, s22, 6
	s_add_i32 s10, s10, s25
	s_lshl_b32 s10, s10, 9
	s_add_u32 s48, s12, s10
	s_addc_u32 s49, s13, 0
	global_load_dwordx4 v[36:39], v5, s[46:47] offset:0
	global_load_dwordx4 v[40:43], v5, s[46:47] offset:32
	global_load_dwordx4 v[44:47], v5, s[46:47] offset:2048
	global_load_dwordx4 v[48:51], v5, s[46:47] offset:2080
	global_load_dwordx2 v[24:25], v6, s[48:49] offset:0
	global_load_dwordx2 v[26:27], v6, s[48:49] offset:256
	s_waitcnt vmcnt(0)
.Lp6_have_g:
	s_mul_i32 s10, s22, 0x108
	s_add_i32 s10, s10, s6
	s_lshl_b32 s10, s10, 6
	s_add_i32 s10, s10, s25
	s_lshl_b32 s10, s10, 9
	s_add_u32 s40, s44, s10
	s_addc_u32 s41, s45, 0
	v_mov_b32_e32 v12, 0
	v_mov_b32_e32 v13, 0
	v_mov_b32_e32 v14, 0
	v_mov_b32_e32 v15, 0
	v_mfma_f32_32x32x16_f16 v[96:111], v[52:55], v[36:39], 0
	v_mfma_f32_32x32x16_f16 v[112:127], v[52:55], v[40:43], 0
	v_mfma_f32_32x32x16_f16 v[128:143], v[52:55], v[44:47], 0
	v_mfma_f32_32x32x16_f16 v[144:159], v[52:55], v[48:51], 0
	s_nop 15
	v_fma_f32 v20, v24, v12, v96
	v_fma_f32 v21, v24, v13, v112
	v_fma_f32 v22, v26, v14, v128
	v_fma_f32 v23, v26, v15, v144
	v_fma_f32 v16, -v25, v13, v20
	v_fma_f32 v17, v25, v12, v21
	v_fma_f32 v18, -v27, v15, v22
	v_fma_f32 v19, v27, v14, v23
	v_fma_f32 v20, v24, v16, v97
	v_fma_f32 v21, v24, v17, v113
	v_fma_f32 v22, v26, v18, v129
	v_fma_f32 v23, v26, v19, v145
	v_fma_f32 v12, -v25, v17, v20
	v_fma_f32 v13, v25, v16, v21
	v_fma_f32 v14, -v27, v19, v22
	v_fma_f32 v15, v27, v18, v23
	v_fma_f32 v20, v24, v12, v98
	v_fma_f32 v21, v24, v13, v114
	v_fma_f32 v22, v26, v14, v130
	v_fma_f32 v23, v26, v15, v146
	v_fma_f32 v16, -v25, v13, v20
	v_fma_f32 v17, v25, v12, v21
	v_fma_f32 v18, -v27, v15, v22
	v_fma_f32 v19, v27, v14, v23
	v_fma_f32 v20, v24, v16, v99
	v_fma_f32 v21, v24, v17, v115
	v_fma_f32 v22, v26, v18, v131
	v_fma_f32 v23, v26, v19, v147
	v_fma_f32 v12, -v25, v17, v20
	v_fma_f32 v13, v25, v16, v21
	v_fma_f32 v14, -v27, v19, v22
	v_fma_f32 v15, v27, v18, v23
	v_fma_f32 v20, v24, v12, v100
	v_fma_f32 v21, v24, v13, v116
	v_fma_f32 v22, v26, v14, v132
	v_fma_f32 v23, v26, v15, v148
	v_fma_f32 v16, -v25, v13, v20
	v_fma_f32 v17, v25, v12, v21
	v_fma_f32 v18, -v27, v15, v22
	v_fma_f32 v19, v27, v14, v23
	v_fma_f32 v20, v24, v16, v101
	v_fma_f32 v21, v24, v17, v117
	v_fma_f32 v22, v26, v18, v133
	v_fma_f32 v23, v26, v19, v149
	v_fma_f32 v12, -v25, v17, v20
	v_fma_f32 v13, v25, v16, v21
	v_fma_f32 v14, -v27, v19, v22
	v_fma_f32 v15, v27, v18, v23
	v_fma_f32 v20, v24, v12, v102
	v_fma_f32 v21, v24, v13, v118
	v_fma_f32 v22, v26, v14, v134
	v_fma_f32 v23, v26, v15, v150
	v_fma_f32 v16, -v25, v13, v20
	v_fma_f32 v17, v25, v12, v21
	v_fma_f32 v18, -v27, v15, v22
	v_fma_f32 v19, v27, v14, v23
	v_fma_f32 v20, v24, v16, v103
	v_fma_f32 v21, v24, v17, v119
	v_fma_f32 v22, v26, v18, v135
	v_fma_f32 v23, v26, v19, v151
	v_fma_f32 v12, -v25, v17, v20
	v_fma_f32 v13, v25, v16, v21
	v_fma_f32 v14, -v27, v19, v22
	v_fma_f32 v15, v27, v18, v23
	v_fma_f32 v20, v24, v12, v104
	v_fma_f32 v21, v24, v13, v120
	v_fma_f32 v22, v26, v14, v136
	v_fma_f32 v23, v26, v15, v152
	v_fma_f32 v16, -v25, v13, v20
	v_fma_f32 v17, v25, v12, v21
	v_fma_f32 v18, -v27, v15, v22
	v_fma_f32 v19, v27, v14, v23
	v_fma_f32 v20, v24, v16, v105
	v_fma_f32 v21, v24, v17, v121
	v_fma_f32 v22, v26, v18, v137
	v_fma_f32 v23, v26, v19, v153
	v_fma_f32 v12, -v25, v17, v20
	v_fma_f32 v13, v25, v16, v21
	v_fma_f32 v14, -v27, v19, v22
	v_fma_f32 v15, v27, v18, v23
	v_fma_f32 v20, v24, v12, v106
	v_fma_f32 v21, v24, v13, v122
	v_fma_f32 v22, v26, v14, v138
	v_fma_f32 v23, v26, v15, v154
	v_fma_f32 v16, -v25, v13, v20
	v_fma_f32 v17, v25, v12, v21
	v_fma_f32 v18, -v27, v15, v22
	v_fma_f32 v19, v27, v14, v23
	v_fma_f32 v20, v24, v16, v107
	v_fma_f32 v21, v24, v17, v123
	v_fma_f32 v22, v26, v18, v139
	v_fma_f32 v23, v26, v19, v155
	v_fma_f32 v12, -v25, v17, v20
	v_fma_f32 v13, v25, v16, v21
	v_fma_f32 v14, -v27, v19, v22
	v_fma_f32 v15, v27, v18, v23
	v_fma_f32 v20, v24, v12, v108
	v_fma_f32 v21, v24, v13, v124
	v_fma_f32 v22, v26, v14, v140
	v_fma_f32 v23, v26, v15, v156
	v_fma_f32 v16, -v25, v13, v20
	v_fma_f32 v17, v25, v12, v21
	v_fma_f32 v18, -v27, v15, v22
	v_fma_f32 v19, v27, v14, v23
	v_fma_f32 v20, v24, v16, v109
	v_fma_f32 v21, v24, v17, v125
	v_fma_f32 v22, v26, v18, v141
	v_fma_f32 v23, v26, v19, v157
	v_fma_f32 v12, -v25, v17, v20
	v_fma_f32 v13, v25, v16, v21
	v_fma_f32 v14, -v27, v19, v22
	v_fma_f32 v15, v27, v18, v23
	v_fma_f32 v20, v24, v12, v110
	v_fma_f32 v21, v24, v13, v126
	v_fma_f32 v22, v26, v14, v142
	v_fma_f32 v23, v26, v15, v158
	v_fma_f32 v16, -v25, v13, v20
	v_fma_f32 v17, v25, v12, v21
	v_fma_f32 v18, -v27, v15, v22
	v_fma_f32 v19, v27, v14, v23
	v_fma_f32 v20, v24, v16, v111
	v_fma_f32 v21, v24, v17, v127
	v_fma_f32 v22, v26, v18, v143
	v_fma_f32 v23, v26, v19, v159
	v_fma_f32 v12, -v25, v17, v20
	v_fma_f32 v13, v25, v16, v21
	v_fma_f32 v14, -v27, v19, v22
	v_fma_f32 v15, v27, v18, v23
	v_mfma_f32_32x32x16_f16 v[96:111], v[56:59], v[36:39], 0
	v_mfma_f32_32x32x16_f16 v[112:127], v[56:59], v[40:43], 0
	v_mfma_f32_32x32x16_f16 v[128:143], v[56:59], v[44:47], 0
	v_mfma_f32_32x32x16_f16 v[144:159], v[56:59], v[48:51], 0
	s_nop 15
	v_fma_f32 v20, v24, v12, v96
	v_fma_f32 v21, v24, v13, v112
	v_fma_f32 v22, v26, v14, v128
	v_fma_f32 v23, v26, v15, v144
	v_fma_f32 v16, -v25, v13, v20
	v_fma_f32 v17, v25, v12, v21
	v_fma_f32 v18, -v27, v15, v22
	v_fma_f32 v19, v27, v14, v23
	v_fma_f32 v20, v24, v16, v97
	v_fma_f32 v21, v24, v17, v113
	v_fma_f32 v22, v26, v18, v129
	v_fma_f32 v23, v26, v19, v145
	v_fma_f32 v12, -v25, v17, v20
	v_fma_f32 v13, v25, v16, v21
	v_fma_f32 v14, -v27, v19, v22
	v_fma_f32 v15, v27, v18, v23
	v_fma_f32 v20, v24, v12, v98
	v_fma_f32 v21, v24, v13, v114
	v_fma_f32 v22, v26, v14, v130
	v_fma_f32 v23, v26, v15, v146
	v_fma_f32 v16, -v25, v13, v20
	v_fma_f32 v17, v25, v12, v21
	v_fma_f32 v18, -v27, v15, v22
	v_fma_f32 v19, v27, v14, v23
	v_fma_f32 v20, v24, v16, v99
	v_fma_f32 v21, v24, v17, v115
	v_fma_f32 v22, v26, v18, v131
	v_fma_f32 v23, v26, v19, v147
	v_fma_f32 v12, -v25, v17, v20
	v_fma_f32 v13, v25, v16, v21
	v_fma_f32 v14, -v27, v19, v22
	v_fma_f32 v15, v27, v18, v23
	v_fma_f32 v20, v24, v12, v100
	v_fma_f32 v21, v24, v13, v116
	v_fma_f32 v22, v26, v14, v132
	v_fma_f32 v23, v26, v15, v148
	v_fma_f32 v16, -v25, v13, v20
	v_fma_f32 v17, v25, v12, v21
	v_fma_f32 v18, -v27, v15, v22
	v_fma_f32 v19, v27, v14, v23
	v_fma_f32 v20, v24, v16, v101
	v_fma_f32 v21, v24, v17, v117
	v_fma_f32 v22, v26, v18, v133
	v_fma_f32 v23, v26, v19, v149
	v_fma_f32 v12, -v25, v17, v20
	v_fma_f32 v13, v25, v16, v21
	v_fma_f32 v14, -v27, v19, v22
	v_fma_f32 v15, v27, v18, v23
	v_fma_f32 v20, v24, v12, v102
	v_fma_f32 v21, v24, v13, v118
	v_fma_f32 v22, v26, v14, v134
	v_fma_f32 v23, v26, v15, v150
	v_fma_f32 v16, -v25, v13, v20
	v_fma_f32 v17, v25, v12, v21
	v_fma_f32 v18, -v27, v15, v22
	v_fma_f32 v19, v27, v14, v23
	v_fma_f32 v20, v24, v16, v103
	v_fma_f32 v21, v24, v17, v119
	v_fma_f32 v22, v26, v18, v135
	v_fma_f32 v23, v26, v19, v151
	v_fma_f32 v12, -v25, v17, v20
	v_fma_f32 v13, v25, v16, v21
	v_fma_f32 v14, -v27, v19, v22
	v_fma_f32 v15, v27, v18, v23
	v_fma_f32 v20, v24, v12, v104
	v_fma_f32 v21, v24, v13, v120
	v_fma_f32 v22, v26, v14, v136
	v_fma_f32 v23, v26, v15, v152
	v_fma_f32 v16, -v25, v13, v20
	v_fma_f32 v17, v25, v12, v21
	v_fma_f32 v18, -v27, v15, v22
	v_fma_f32 v19, v27, v14, v23
	v_fma_f32 v20, v24, v16, v105
	v_fma_f32 v21, v24, v17, v121
	v_fma_f32 v22, v26, v18, v137
	v_fma_f32 v23, v26, v19, v153
	v_fma_f32 v12, -v25, v17, v20
	v_fma_f32 v13, v25, v16, v21
	v_fma_f32 v14, -v27, v19, v22
	v_fma_f32 v15, v27, v18, v23
	v_fma_f32 v20, v24, v12, v106
	v_fma_f32 v21, v24, v13, v122
	v_fma_f32 v22, v26, v14, v138
	v_fma_f32 v23, v26, v15, v154
	v_fma_f32 v16, -v25, v13, v20
	v_fma_f32 v17, v25, v12, v21
	v_fma_f32 v18, -v27, v15, v22
	v_fma_f32 v19, v27, v14, v23
	v_fma_f32 v20, v24, v16, v107
	v_fma_f32 v21, v24, v17, v123
	v_fma_f32 v22, v26, v18, v139
	v_fma_f32 v23, v26, v19, v155
	v_fma_f32 v12, -v25, v17, v20
	v_fma_f32 v13, v25, v16, v21
	v_fma_f32 v14, -v27, v19, v22
	v_fma_f32 v15, v27, v18, v23
	v_fma_f32 v20, v24, v12, v108
	v_fma_f32 v21, v24, v13, v124
	v_fma_f32 v22, v26, v14, v140
	v_fma_f32 v23, v26, v15, v156
	v_fma_f32 v16, -v25, v13, v20
	v_fma_f32 v17, v25, v12, v21
	v_fma_f32 v18, -v27, v15, v22
	v_fma_f32 v19, v27, v14, v23
	v_fma_f32 v20, v24, v16, v109
	v_fma_f32 v21, v24, v17, v125
	v_fma_f32 v22, v26, v18, v141
	v_fma_f32 v23, v26, v19, v157
	v_fma_f32 v12, -v25, v17, v20
	v_fma_f32 v13, v25, v16, v21
	v_fma_f32 v14, -v27, v19, v22
	v_fma_f32 v15, v27, v18, v23
	v_fma_f32 v20, v24, v12, v110
	v_fma_f32 v21, v24, v13, v126
	v_fma_f32 v22, v26, v14, v142
	v_fma_f32 v23, v26, v15, v158
	v_fma_f32 v16, -v25, v13, v20
	v_fma_f32 v17, v25, v12, v21
	v_fma_f32 v18, -v27, v15, v22
	v_fma_f32 v19, v27, v14, v23
	v_fma_f32 v20, v24, v16, v111
	v_fma_f32 v21, v24, v17, v127
	v_fma_f32 v22, v26, v18, v143
	v_fma_f32 v23, v26, v19, v159
	v_fma_f32 v12, -v25, v17, v20
	v_fma_f32 v13, v25, v16, v21
	v_fma_f32 v14, -v27, v19, v22
	v_fma_f32 v15, v27, v18, v23
	v_mfma_f32_32x32x16_f16 v[96:111], v[60:63], v[36:39], 0
	v_mfma_f32_32x32x16_f16 v[112:127], v[60:63], v[40:43], 0
	v_mfma_f32_32x32x16_f16 v[128:143], v[60:63], v[44:47], 0
	v_mfma_f32_32x32x16_f16 v[144:159], v[60:63], v[48:51], 0
	s_nop 15
	v_fma_f32 v20, v24, v12, v96
	v_fma_f32 v21, v24, v13, v112
	v_fma_f32 v22, v26, v14, v128
	v_fma_f32 v23, v26, v15, v144
	v_fma_f32 v16, -v25, v13, v20
	v_fma_f32 v17, v25, v12, v21
	v_fma_f32 v18, -v27, v15, v22
	v_fma_f32 v19, v27, v14, v23
	v_fma_f32 v20, v24, v16, v97
	v_fma_f32 v21, v24, v17, v113
	v_fma_f32 v22, v26, v18, v129
	v_fma_f32 v23, v26, v19, v145
	v_fma_f32 v12, -v25, v17, v20
	v_fma_f32 v13, v25, v16, v21
	v_fma_f32 v14, -v27, v19, v22
	v_fma_f32 v15, v27, v18, v23
	v_fma_f32 v20, v24, v12, v98
	v_fma_f32 v21, v24, v13, v114
	v_fma_f32 v22, v26, v14, v130
	v_fma_f32 v23, v26, v15, v146
	v_fma_f32 v16, -v25, v13, v20
	v_fma_f32 v17, v25, v12, v21
	v_fma_f32 v18, -v27, v15, v22
	v_fma_f32 v19, v27, v14, v23
	v_fma_f32 v20, v24, v16, v99
	v_fma_f32 v21, v24, v17, v115
	v_fma_f32 v22, v26, v18, v131
	v_fma_f32 v23, v26, v19, v147
	v_fma_f32 v12, -v25, v17, v20
	v_fma_f32 v13, v25, v16, v21
	v_fma_f32 v14, -v27, v19, v22
	v_fma_f32 v15, v27, v18, v23
	v_fma_f32 v20, v24, v12, v100
	v_fma_f32 v21, v24, v13, v116
	v_fma_f32 v22, v26, v14, v132
	v_fma_f32 v23, v26, v15, v148
	v_fma_f32 v16, -v25, v13, v20
	v_fma_f32 v17, v25, v12, v21
	v_fma_f32 v18, -v27, v15, v22
	v_fma_f32 v19, v27, v14, v23
	v_fma_f32 v20, v24, v16, v101
	v_fma_f32 v21, v24, v17, v117
	v_fma_f32 v22, v26, v18, v133
	v_fma_f32 v23, v26, v19, v149
	v_fma_f32 v12, -v25, v17, v20
	v_fma_f32 v13, v25, v16, v21
	v_fma_f32 v14, -v27, v19, v22
	v_fma_f32 v15, v27, v18, v23
	v_fma_f32 v20, v24, v12, v102
	v_fma_f32 v21, v24, v13, v118
	v_fma_f32 v22, v26, v14, v134
	v_fma_f32 v23, v26, v15, v150
	v_fma_f32 v16, -v25, v13, v20
	v_fma_f32 v17, v25, v12, v21
	v_fma_f32 v18, -v27, v15, v22
	v_fma_f32 v19, v27, v14, v23
	v_fma_f32 v20, v24, v16, v103
	v_fma_f32 v21, v24, v17, v119
	v_fma_f32 v22, v26, v18, v135
	v_fma_f32 v23, v26, v19, v151
	v_fma_f32 v12, -v25, v17, v20
	v_fma_f32 v13, v25, v16, v21
	v_fma_f32 v14, -v27, v19, v22
	v_fma_f32 v15, v27, v18, v23
	v_fma_f32 v20, v24, v12, v104
	v_fma_f32 v21, v24, v13, v120
	v_fma_f32 v22, v26, v14, v136
	v_fma_f32 v23, v26, v15, v152
	v_fma_f32 v16, -v25, v13, v20
	v_fma_f32 v17, v25, v12, v21
	v_fma_f32 v18, -v27, v15, v22
	v_fma_f32 v19, v27, v14, v23
	v_fma_f32 v20, v24, v16, v105
	v_fma_f32 v21, v24, v17, v121
	v_fma_f32 v22, v26, v18, v137
	v_fma_f32 v23, v26, v19, v153
	v_fma_f32 v12, -v25, v17, v20
	v_fma_f32 v13, v25, v16, v21
	v_fma_f32 v14, -v27, v19, v22
	v_fma_f32 v15, v27, v18, v23
	v_fma_f32 v20, v24, v12, v106
	v_fma_f32 v21, v24, v13, v122
	v_fma_f32 v22, v26, v14, v138
	v_fma_f32 v23, v26, v15, v154
	v_fma_f32 v16, -v25, v13, v20
	v_fma_f32 v17, v25, v12, v21
	v_fma_f32 v18, -v27, v15, v22
	v_fma_f32 v19, v27, v14, v23
	v_fma_f32 v20, v24, v16, v107
	v_fma_f32 v21, v24, v17, v123
	v_fma_f32 v22, v26, v18, v139
	v_fma_f32 v23, v26, v19, v155
	v_fma_f32 v12, -v25, v17, v20
	v_fma_f32 v13, v25, v16, v21
	v_fma_f32 v14, -v27, v19, v22
	v_fma_f32 v15, v27, v18, v23
	v_fma_f32 v20, v24, v12, v108
	v_fma_f32 v21, v24, v13, v124
	v_fma_f32 v22, v26, v14, v140
	v_fma_f32 v23, v26, v15, v156
	v_fma_f32 v16, -v25, v13, v20
	v_fma_f32 v17, v25, v12, v21
	v_fma_f32 v18, -v27, v15, v22
	v_fma_f32 v19, v27, v14, v23
	v_fma_f32 v20, v24, v16, v109
	v_fma_f32 v21, v24, v17, v125
	v_fma_f32 v22, v26, v18, v141
	v_fma_f32 v23, v26, v19, v157
	v_fma_f32 v12, -v25, v17, v20
	v_fma_f32 v13, v25, v16, v21
	v_fma_f32 v14, -v27, v19, v22
	v_fma_f32 v15, v27, v18, v23
	v_fma_f32 v20, v24, v12, v110
	v_fma_f32 v21, v24, v13, v126
	v_fma_f32 v22, v26, v14, v142
	v_fma_f32 v23, v26, v15, v158
	v_fma_f32 v16, -v25, v13, v20
	v_fma_f32 v17, v25, v12, v21
	v_fma_f32 v18, -v27, v15, v22
	v_fma_f32 v19, v27, v14, v23
	v_fma_f32 v20, v24, v16, v111
	v_fma_f32 v21, v24, v17, v127
	v_fma_f32 v22, v26, v18, v143
	v_fma_f32 v23, v26, v19, v159
	v_fma_f32 v12, -v25, v17, v20
	v_fma_f32 v13, v25, v16, v21
	v_fma_f32 v14, -v27, v19, v22
	v_fma_f32 v15, v27, v18, v23
	v_mfma_f32_32x32x16_f16 v[96:111], v[64:67], v[36:39], 0
	v_mfma_f32_32x32x16_f16 v[112:127], v[64:67], v[40:43], 0
	v_mfma_f32_32x32x16_f16 v[128:143], v[64:67], v[44:47], 0
	v_mfma_f32_32x32x16_f16 v[144:159], v[64:67], v[48:51], 0
	s_nop 15
	v_fma_f32 v20, v24, v12, v96
	v_fma_f32 v21, v24, v13, v112
	v_fma_f32 v22, v26, v14, v128
	v_fma_f32 v23, v26, v15, v144
	v_fma_f32 v16, -v25, v13, v20
	v_fma_f32 v17, v25, v12, v21
	v_fma_f32 v18, -v27, v15, v22
	v_fma_f32 v19, v27, v14, v23
	v_fma_f32 v20, v24, v16, v97
	v_fma_f32 v21, v24, v17, v113
	v_fma_f32 v22, v26, v18, v129
	v_fma_f32 v23, v26, v19, v145
	v_fma_f32 v12, -v25, v17, v20
	v_fma_f32 v13, v25, v16, v21
	v_fma_f32 v14, -v27, v19, v22
	v_fma_f32 v15, v27, v18, v23
	v_fma_f32 v20, v24, v12, v98
	v_fma_f32 v21, v24, v13, v114
	v_fma_f32 v22, v26, v14, v130
	v_fma_f32 v23, v26, v15, v146
	v_fma_f32 v16, -v25, v13, v20
	v_fma_f32 v17, v25, v12, v21
	v_fma_f32 v18, -v27, v15, v22
	v_fma_f32 v19, v27, v14, v23
	v_fma_f32 v20, v24, v16, v99
	v_fma_f32 v21, v24, v17, v115
	v_fma_f32 v22, v26, v18, v131
	v_fma_f32 v23, v26, v19, v147
	v_fma_f32 v12, -v25, v17, v20
	v_fma_f32 v13, v25, v16, v21
	v_fma_f32 v14, -v27, v19, v22
	v_fma_f32 v15, v27, v18, v23
	v_fma_f32 v20, v24, v12, v100
	v_fma_f32 v21, v24, v13, v116
	v_fma_f32 v22, v26, v14, v132
	v_fma_f32 v23, v26, v15, v148
	v_fma_f32 v16, -v25, v13, v20
	v_fma_f32 v17, v25, v12, v21
	v_fma_f32 v18, -v27, v15, v22
	v_fma_f32 v19, v27, v14, v23
	v_fma_f32 v20, v24, v16, v101
	v_fma_f32 v21, v24, v17, v117
	v_fma_f32 v22, v26, v18, v133
	v_fma_f32 v23, v26, v19, v149
	v_fma_f32 v12, -v25, v17, v20
	v_fma_f32 v13, v25, v16, v21
	v_fma_f32 v14, -v27, v19, v22
	v_fma_f32 v15, v27, v18, v23
	v_fma_f32 v20, v24, v12, v102
	v_fma_f32 v21, v24, v13, v118
	v_fma_f32 v22, v26, v14, v134
	v_fma_f32 v23, v26, v15, v150
	v_fma_f32 v16, -v25, v13, v20
	v_fma_f32 v17, v25, v12, v21
	v_fma_f32 v18, -v27, v15, v22
	v_fma_f32 v19, v27, v14, v23
	v_fma_f32 v20, v24, v16, v103
	v_fma_f32 v21, v24, v17, v119
	v_fma_f32 v22, v26, v18, v135
	v_fma_f32 v23, v26, v19, v151
	v_fma_f32 v12, -v25, v17, v20
	v_fma_f32 v13, v25, v16, v21
	v_fma_f32 v14, -v27, v19, v22
	v_fma_f32 v15, v27, v18, v23
	v_fma_f32 v20, v24, v12, v104
	v_fma_f32 v21, v24, v13, v120
	v_fma_f32 v22, v26, v14, v136
	v_fma_f32 v23, v26, v15, v152
	v_fma_f32 v16, -v25, v13, v20
	v_fma_f32 v17, v25, v12, v21
	v_fma_f32 v18, -v27, v15, v22
	v_fma_f32 v19, v27, v14, v23
	v_fma_f32 v20, v24, v16, v105
	v_fma_f32 v21, v24, v17, v121
	v_fma_f32 v22, v26, v18, v137
	v_fma_f32 v23, v26, v19, v153
	v_fma_f32 v12, -v25, v17, v20
	v_fma_f32 v13, v25, v16, v21
	v_fma_f32 v14, -v27, v19, v22
	v_fma_f32 v15, v27, v18, v23
	v_fma_f32 v20, v24, v12, v106
	v_fma_f32 v21, v24, v13, v122
	v_fma_f32 v22, v26, v14, v138
	v_fma_f32 v23, v26, v15, v154
	v_fma_f32 v16, -v25, v13, v20
	v_fma_f32 v17, v25, v12, v21
	v_fma_f32 v18, -v27, v15, v22
	v_fma_f32 v19, v27, v14, v23
	v_fma_f32 v20, v24, v16, v107
	v_fma_f32 v21, v24, v17, v123
	v_fma_f32 v22, v26, v18, v139
	v_fma_f32 v23, v26, v19, v155
	v_fma_f32 v12, -v25, v17, v20
	v_fma_f32 v13, v25, v16, v21
	v_fma_f32 v14, -v27, v19, v22
	v_fma_f32 v15, v27, v18, v23
	v_fma_f32 v20, v24, v12, v108
	v_fma_f32 v21, v24, v13, v124
	v_fma_f32 v22, v26, v14, v140
	v_fma_f32 v23, v26, v15, v156
	v_fma_f32 v16, -v25, v13, v20
	v_fma_f32 v17, v25, v12, v21
	v_fma_f32 v18, -v27, v15, v22
	v_fma_f32 v19, v27, v14, v23
	v_fma_f32 v20, v24, v16, v109
	v_fma_f32 v21, v24, v17, v125
	v_fma_f32 v22, v26, v18, v141
	v_fma_f32 v23, v26, v19, v157
	v_fma_f32 v12, -v25, v17, v20
	v_fma_f32 v13, v25, v16, v21
	v_fma_f32 v14, -v27, v19, v22
	v_fma_f32 v15, v27, v18, v23
	v_fma_f32 v20, v24, v12, v110
	v_fma_f32 v21, v24, v13, v126
	v_fma_f32 v22, v26, v14, v142
	v_fma_f32 v23, v26, v15, v158
	v_fma_f32 v16, -v25, v13, v20
	v_fma_f32 v17, v25, v12, v21
	v_fma_f32 v18, -v27, v15, v22
	v_fma_f32 v19, v27, v14, v23
	v_fma_f32 v20, v24, v16, v111
	v_fma_f32 v21, v24, v17, v127
	v_fma_f32 v22, v26, v18, v143
	v_fma_f32 v23, v26, v19, v159
	v_fma_f32 v12, -v25, v17, v20
	v_fma_f32 v13, v25, v16, v21
	v_fma_f32 v14, -v27, v19, v22
	v_fma_f32 v15, v27, v18, v23
	global_store_dwordx2 v7, v[12:13], s[40:41] offset:0
	global_store_dwordx2 v7, v[14:15], s[40:41] offset:256
	s_cmpk_gt_u32 s5, 0x83f
	s_cbranch_scc0 .Lp6_top

.Lp8_fwd:
	v_lshlrev_b32_e32 v4, 11, v3
	v_lshl_add_u32 v4, v1, 4, v4
	v_lshlrev_b32_e32 v5, 6, v0
	v_lshl_add_u32 v5, v1, 4, v5
	v_lshlrev_b32_e32 v6, 3, v0
	v_mov_b32_e32 v9, 0x420000
	v_mul_lo_u32 v7, v1, v9
	v_lshl_add_u32 v7, v0, 3, v7
	s_mul_i32 s10, s95, 0x2100
	v_lshl_add_u32 v9, v1, 7, v0
	v_lshlrev_b32_e32 v9, 4, v9
	v_add_u32_e32 v84, s10, v9
	v_lshrrev_b32_e32 v9, 2, v93
	v_lshl_add_u32 v9, v94, 3, v9
	v_lshlrev_b32_e32 v9, 4, v9
	v_and_b32_e32 v10, 1, v93
	v_lshl_add_u32 v9, v10, 3, v9
	v_bfe_u32 v10, v93, 1, 1
	v_mov_b32_e32 v85, 0x1040
	v_mul_lo_u32 v10, v10, v85
	v_add3_u32 v85, v9, v10, s10
	v_lshlrev_b32_e32 v86, 8, v93
	v_lshl_add_u32 v86, v94, 5, v86
	s_lshl_b32 s10, s95, 13
	s_add_i32 s10, s10, 0x10800
	v_lshlrev_b32_e32 v9, 6, v95
	v_lshl_add_u32 v9, v94, 4, v9
	v_add_u32_e32 v87, s10, v9
	v_lshrrev_b32_e32 v93, 7, v204
	v_bfe_u32 v94, v204, 1, 6
	v_and_b32_e32 v95, 1, v204
	v_lshlrev_b32_e32 v9, 14, v93
	v_lshl_add_u32 v9, v94, 6, v9
	v_lshl_add_u32 v9, v95, 5, v9
	v_add_u32_e32 v88, 0x10800, v9
	v_lshlrev_b32_e32 v9, 11, v94
	v_lshl_add_u32 v9, v93, 5, v9
	v_lshl_add_u32 v89, v95, 4, v9
	v_lshlrev_b32_e32 v9, 6, v93
	v_lshl_add_u32 v90, v95, 5, v9
	v_and_b32_e32 v9, 1, v0
	v_mov_b32_e32 v10, 0x80000000
	v_cmp_eq_u32_e32 vcc, 0, v9
	s_nop 3
	v_cndmask_b32_e32 v8, 0, v10, vcc
	s_lshl_b32 s10, s95, 2
	s_add_i32 s10, s10, 0x20800
	v_mov_b32_e32 v202, s10
	s_xor_b32 s10, s10, 4
	v_mov_b32_e32 v203, s10
	v_mov_b32_e32 v230, 0
	ds_write_b32 v202, v230
	ds_write_b32 v202, v230 offset:32
	s_mov_b32 s85, 0
	s_waitcnt lgkmcnt(0)
	s_barrier
	s_mov_b32 s27, -1
	s_mov_b32 s5, s8
	s_mov_b32 s35, 1
	s_branch .Lp8_prefetch

.Lp8_prefetch:
	s_lshr_b32 s6, s5, 4
	s_and_b32 s7, s5, 15
	s_lshl_b32 s11, s7, 2
	s_add_i32 s11, s11, s20
	s_mul_i32 s10, s22, 0x108
	s_add_i32 s10, s10, s6
	s_lshl_b32 s10, s10, 6
	s_add_i32 s10, s10, s11
	s_lshl_b32 s10, s10, 9
	s_add_u32 s40, s44, s10
	s_addc_u32 s41, s45, 0
	s_lshl_b32 s11, s11, 5
	s_cmp_lt_u32 s6, 4
	s_mov_b32 s10, 0x80000
	s_cselect_b32 s33, s10, 0x1000000
	s_movk_i32 s10, 0x4000
	s_cselect_b32 s32, s10, 0xffffff00
	s_lshl_b32 s10, s6, 6
	s_add_i32 s32, s32, s10
	s_lshl_b32 s32, s32, 11
	s_add_i32 s32, s32, s11
	v_mul_lo_u32 v9, v2, s33
	v_add3_u32 v11, v4, v9, s32
	global_load_dwordx4 v[68:71], v11, s[54:55]
	global_load_dwordx4 v[72:75], v11, s[56:57]
	global_load_dwordx4 v[76:79], v11, s[58:59]
	global_load_dwordx4 v[80:83], v11, s[66:67]
	global_load_dwordx2 v[28:29], v7, s[40:41] offset:0
	global_load_dwordx2 v[30:31], v7, s[40:41] offset:256
	s_cmp_eq_u32 s35, 0
	s_cbranch_scc1 .Lp8_compute
	s_mov_b32 s35, 0
	s_waitcnt vmcnt(0)
	s_branch .Lp8_top_body
.Lp8_compute:
	s_lshr_b32 s6, s4, 4
	s_and_b32 s7, s4, 15
	s_cmp_eq_u32 s7, s27
	s_cbranch_scc1 .Lp8_have_g
	s_mov_b32 s27, s7
	s_lshl_b32 s25, s7, 2
	s_add_i32 s25, s25, s20
	s_lshl_b32 s10, s25, 1
	s_add_i32 s10, s10, s22
	s_lshl_b32 s10, s10, 12
	s_add_u32 s46, s14, s10
	s_addc_u32 s47, s15, 0
	s_add_u32 s70, s68, s10
	s_addc_u32 s71, s69, 0
	s_lshl_b32 s10, s22, 6
	s_add_i32 s10, s10, s25
	s_lshl_b32 s10, s10, 9
	s_add_u32 s48, s12, s10
	s_addc_u32 s49, s13, 0
	s_lshl_b32 s10, s7, 8
	s_add_u32 s72, s2, s10
	s_addc_u32 s73, s3, 0
	global_load_dwordx4 v[36:39], v5, s[46:47] offset:0
	global_load_dwordx4 v[40:43], v5, s[46:47] offset:32
	global_load_dwordx4 v[44:47], v5, s[46:47] offset:2048
	global_load_dwordx4 v[48:51], v5, s[46:47] offset:2080
	global_load_dwordx4 v[194:197], v86, s[70:71] offset:0
	global_load_dwordx4 v[198:201], v86, s[70:71] offset:16
	global_load_dwordx4 v[206:209], v86, s[70:71] offset:128
	global_load_dwordx4 v[210:213], v86, s[70:71] offset:144
	global_load_dwordx2 v[24:25], v6, s[48:49] offset:0
	global_load_dwordx2 v[26:27], v6, s[48:49] offset:256
	global_load_dwordx4 v[222:225], v90, s[72:73]
	global_load_dwordx4 v[226:229], v90, s[72:73] offset:16
	s_waitcnt vmcnt(0)
	s_mov_b32 s65, 0x5040100
	s_mov_b32 s11, 0x7060302
	v_perm_b32 v160, v195, v194, s65
	v_perm_b32 v164, v195, v194, s11
	v_perm_b32 v161, v197, v196, s65
	v_perm_b32 v165, v197, v196, s11
	v_perm_b32 v162, v199, v198, s65
	v_perm_b32 v166, v199, v198, s11
	v_perm_b32 v163, v201, v200, s65
	v_perm_b32 v167, v201, v200, s11
	v_perm_b32 v168, v207, v206, s65
	v_perm_b32 v172, v207, v206, s11
	v_perm_b32 v169, v209, v208, s65
	v_perm_b32 v173, v209, v208, s11
	v_perm_b32 v170, v211, v210, s65
	v_perm_b32 v174, v211, v210, s11
	v_perm_b32 v171, v213, v212, s65
	v_perm_b32 v175, v213, v212, s11
.Lp8_have_g:
	s_cmp_lt_u32 s6, 4
	s_mov_b32 s10, 0x80000
	s_cselect_b32 s84, s10, 0x1000000
	s_movk_i32 s10, 0x4000
	s_cselect_b32 s83, s10, 0xffffff00
	s_lshl_b32 s10, s6, 6
	s_add_i32 s83, s83, s10
	s_lshl_b32 s83, s83, 11
	s_lshl_b32 s10, s7, 7
	s_add_i32 s83, s83, s10
	v_add_u32_e32 v91, s83, v89
	v_add_u32_e32 v92, s84, v91
	global_load_dwordx4 v[214:217], v91, s[36:37]
	global_load_dwordx4 v[218:221], v92, s[36:37]
	v_mfma_f32_32x32x16_f16 v[96:111], v[52:55], v[36:39], 0
	v_mfma_f32_32x32x16_f16 v[112:127], v[52:55], v[40:43], 0
	v_mfma_f32_32x32x16_f16 v[128:143], v[52:55], v[44:47], 0
	v_mfma_f32_32x32x16_f16 v[144:159], v[52:55], v[48:51], 0
	s_nop 15
	v_fma_f32 v20, v24, v12, v96
	v_fma_f32 v21, v24, v13, v112
	v_fma_f32 v22, v26, v14, v128
	v_fma_f32 v23, v26, v15, v144
	v_fma_f32 v16, -v25, v13, v20
	v_fma_f32 v17, v25, v12, v21
	v_fma_f32 v18, -v27, v15, v22
	v_fma_f32 v19, v27, v14, v23
	v_fma_f32 v20, v24, v16, v97
	v_fma_f32 v21, v24, v17, v113
	v_fma_f32 v22, v26, v18, v129
	v_fma_f32 v23, v26, v19, v145
	v_fma_f32 v12, -v25, v17, v20
	v_fma_f32 v13, v25, v16, v21
	v_fma_f32 v14, -v27, v19, v22
	v_fma_f32 v15, v27, v18, v23
	v_cvt_pk_f16_f32 v178, v16, v12
	v_cvt_pk_f16_f32 v182, v17, v13
	v_cvt_pk_f16_f32 v186, v18, v14
	v_cvt_pk_f16_f32 v190, v19, v15
	v_fma_f32 v20, v24, v12, v98
	v_fma_f32 v21, v24, v13, v114
	v_fma_f32 v22, v26, v14, v130
	v_fma_f32 v23, v26, v15, v146
	v_fma_f32 v16, -v25, v13, v20
	v_fma_f32 v17, v25, v12, v21
	v_fma_f32 v18, -v27, v15, v22
	v_fma_f32 v19, v27, v14, v23
	v_fma_f32 v20, v24, v16, v99
	v_fma_f32 v21, v24, v17, v115
	v_fma_f32 v22, v26, v18, v131
	v_fma_f32 v23, v26, v19, v147
	v_fma_f32 v12, -v25, v17, v20
	v_fma_f32 v13, v25, v16, v21
	v_fma_f32 v14, -v27, v19, v22
	v_fma_f32 v15, v27, v18, v23
	v_cvt_pk_f16_f32 v179, v16, v12
	v_cvt_pk_f16_f32 v183, v17, v13
	v_cvt_pk_f16_f32 v187, v18, v14
	v_cvt_pk_f16_f32 v191, v19, v15
	v_fma_f32 v20, v24, v12, v100
	v_fma_f32 v21, v24, v13, v116
	v_fma_f32 v22, v26, v14, v132
	v_fma_f32 v23, v26, v15, v148
	v_fma_f32 v16, -v25, v13, v20
	v_fma_f32 v17, v25, v12, v21
	v_fma_f32 v18, -v27, v15, v22
	v_fma_f32 v19, v27, v14, v23
	v_fma_f32 v20, v24, v16, v101
	v_fma_f32 v21, v24, v17, v117
	v_fma_f32 v22, v26, v18, v133
	v_fma_f32 v23, v26, v19, v149
	v_fma_f32 v12, -v25, v17, v20
	v_fma_f32 v13, v25, v16, v21
	v_fma_f32 v14, -v27, v19, v22
	v_fma_f32 v15, v27, v18, v23
	v_cvt_pk_f16_f32 v180, v16, v12
	v_cvt_pk_f16_f32 v184, v17, v13
	v_cvt_pk_f16_f32 v188, v18, v14
	v_cvt_pk_f16_f32 v192, v19, v15
	v_fma_f32 v20, v24, v12, v102
	v_fma_f32 v21, v24, v13, v118
	v_fma_f32 v22, v26, v14, v134
	v_fma_f32 v23, v26, v15, v150
	v_fma_f32 v16, -v25, v13, v20
	v_fma_f32 v17, v25, v12, v21
	v_fma_f32 v18, -v27, v15, v22
	v_fma_f32 v19, v27, v14, v23
	v_fma_f32 v20, v24, v16, v103
	v_fma_f32 v21, v24, v17, v119
	v_fma_f32 v22, v26, v18, v135
	v_fma_f32 v23, v26, v19, v151
	v_fma_f32 v12, -v25, v17, v20
	v_fma_f32 v13, v25, v16, v21
	v_fma_f32 v14, -v27, v19, v22
	v_fma_f32 v15, v27, v18, v23
	v_cvt_pk_f16_f32 v181, v16, v12
	v_cvt_pk_f16_f32 v185, v17, v13
	v_cvt_pk_f16_f32 v189, v18, v14
	v_cvt_pk_f16_f32 v193, v19, v15
	ds_write_b128 v84, v[178:181] offset:0
	ds_write_b128 v84, v[182:185] offset:512
	ds_write_b128 v84, v[186:189] offset:1024
	ds_write_b128 v84, v[190:193] offset:1536
	v_fma_f32 v20, v24, v12, v104
	v_fma_f32 v21, v24, v13, v120
	v_fma_f32 v22, v26, v14, v136
	v_fma_f32 v23, v26, v15, v152
	v_fma_f32 v16, -v25, v13, v20
	v_fma_f32 v17, v25, v12, v21
	v_fma_f32 v18, -v27, v15, v22
	v_fma_f32 v19, v27, v14, v23
	v_fma_f32 v20, v24, v16, v105
	v_fma_f32 v21, v24, v17, v121
	v_fma_f32 v22, v26, v18, v137
	v_fma_f32 v23, v26, v19, v153
	v_fma_f32 v12, -v25, v17, v20
	v_fma_f32 v13, v25, v16, v21
	v_fma_f32 v14, -v27, v19, v22
	v_fma_f32 v15, v27, v18, v23
	v_cvt_pk_f16_f32 v178, v16, v12
	v_cvt_pk_f16_f32 v182, v17, v13
	v_cvt_pk_f16_f32 v186, v18, v14
	v_cvt_pk_f16_f32 v190, v19, v15
	v_fma_f32 v20, v24, v12, v106
	v_fma_f32 v21, v24, v13, v122
	v_fma_f32 v22, v26, v14, v138
	v_fma_f32 v23, v26, v15, v154
	v_fma_f32 v16, -v25, v13, v20
	v_fma_f32 v17, v25, v12, v21
	v_fma_f32 v18, -v27, v15, v22
	v_fma_f32 v19, v27, v14, v23
	v_fma_f32 v20, v24, v16, v107
	v_fma_f32 v21, v24, v17, v123
	v_fma_f32 v22, v26, v18, v139
	v_fma_f32 v23, v26, v19, v155
	v_fma_f32 v12, -v25, v17, v20
	v_fma_f32 v13, v25, v16, v21
	v_fma_f32 v14, -v27, v19, v22
	v_fma_f32 v15, v27, v18, v23
	v_cvt_pk_f16_f32 v179, v16, v12
	v_cvt_pk_f16_f32 v183, v17, v13
	v_cvt_pk_f16_f32 v187, v18, v14
	v_cvt_pk_f16_f32 v191, v19, v15
	v_fma_f32 v20, v24, v12, v108
	v_fma_f32 v21, v24, v13, v124
	v_fma_f32 v22, v26, v14, v140
	v_fma_f32 v23, v26, v15, v156
	v_fma_f32 v16, -v25, v13, v20
	v_fma_f32 v17, v25, v12, v21
	v_fma_f32 v18, -v27, v15, v22
	v_fma_f32 v19, v27, v14, v23
	v_fma_f32 v20, v24, v16, v109
	v_fma_f32 v21, v24, v17, v125
	v_fma_f32 v22, v26, v18, v141
	v_fma_f32 v23, v26, v19, v157
	v_fma_f32 v12, -v25, v17, v20
	v_fma_f32 v13, v25, v16, v21
	v_fma_f32 v14, -v27, v19, v22
	v_fma_f32 v15, v27, v18, v23
	v_cvt_pk_f16_f32 v180, v16, v12
	v_cvt_pk_f16_f32 v184, v17, v13
	v_cvt_pk_f16_f32 v188, v18, v14
	v_cvt_pk_f16_f32 v192, v19, v15
	v_fma_f32 v20, v24, v12, v110
	v_fma_f32 v21, v24, v13, v126
	v_fma_f32 v22, v26, v14, v142
	v_fma_f32 v23, v26, v15, v158
	v_fma_f32 v16, -v25, v13, v20
	v_fma_f32 v17, v25, v12, v21
	v_fma_f32 v18, -v27, v15, v22
	v_fma_f32 v19, v27, v14, v23
	v_fma_f32 v20, v24, v16, v111
	v_fma_f32 v21, v24, v17, v127
	v_fma_f32 v22, v26, v18, v143
	v_fma_f32 v23, v26, v19, v159
	v_fma_f32 v12, -v25, v17, v20
	v_fma_f32 v13, v25, v16, v21
	v_fma_f32 v14, -v27, v19, v22
	v_fma_f32 v15, v27, v18, v23
	v_cvt_pk_f16_f32 v181, v16, v12
	v_cvt_pk_f16_f32 v185, v17, v13
	v_cvt_pk_f16_f32 v189, v18, v14
	v_cvt_pk_f16_f32 v193, v19, v15
	ds_write_b128 v84, v[178:181] offset:4160
	ds_write_b128 v84, v[182:185] offset:4672
	ds_write_b128 v84, v[186:189] offset:5184
	ds_write_b128 v84, v[190:193] offset:5696
	v_mfma_f32_32x32x16_f16 v[96:111], v[56:59], v[36:39], 0
	v_mfma_f32_32x32x16_f16 v[112:127], v[56:59], v[40:43], 0
	v_mfma_f32_32x32x16_f16 v[128:143], v[56:59], v[44:47], 0
	v_mfma_f32_32x32x16_f16 v[144:159], v[56:59], v[48:51], 0
	v_add_u32_e32 v93, s76, v87
	ds_read_b64_tr_b16 v[194:195], v85 offset:0
	ds_read_b64_tr_b16 v[196:197], v85 offset:64
	ds_read_b64_tr_b16 v[198:199], v85 offset:512
	ds_read_b64_tr_b16 v[200:201], v85 offset:576
	ds_read_b64_tr_b16 v[206:207], v85 offset:1024
	ds_read_b64_tr_b16 v[208:209], v85 offset:1088
	ds_read_b64_tr_b16 v[210:211], v85 offset:1536
	ds_read_b64_tr_b16 v[212:213], v85 offset:1600
	s_nop 3
	v_fma_f32 v20, v24, v12, v96
	v_fma_f32 v21, v24, v13, v112
	v_fma_f32 v22, v26, v14, v128
	v_fma_f32 v23, v26, v15, v144
	v_fma_f32 v16, -v25, v13, v20
	v_fma_f32 v17, v25, v12, v21
	v_fma_f32 v18, -v27, v15, v22
	v_fma_f32 v19, v27, v14, v23
	v_fma_f32 v20, v24, v16, v97
	v_fma_f32 v21, v24, v17, v113
	v_fma_f32 v22, v26, v18, v129
	v_fma_f32 v23, v26, v19, v145
	v_fma_f32 v12, -v25, v17, v20
	v_fma_f32 v13, v25, v16, v21
	v_fma_f32 v14, -v27, v19, v22
	v_fma_f32 v15, v27, v18, v23
	v_cvt_pk_f16_f32 v178, v16, v12
	v_cvt_pk_f16_f32 v182, v17, v13
	v_cvt_pk_f16_f32 v186, v18, v14
	v_cvt_pk_f16_f32 v190, v19, v15
	s_waitcnt lgkmcnt(6)
	v_mfma_f32_16x16x32_f16 v[32:35], v[160:163], v[194:197], 0
	s_waitcnt lgkmcnt(4)
	v_mfma_f32_16x16x32_f16 v[32:35], v[164:167], v[198:201], v[32:35]
	s_waitcnt lgkmcnt(2)
	v_mfma_f32_16x16x32_f16 v[32:35], v[168:171], v[206:209], v[32:35]
	s_waitcnt lgkmcnt(0)
	v_mfma_f32_16x16x32_f16 v[32:35], v[172:175], v[210:213], v[32:35]
	v_fma_f32 v20, v24, v12, v98
	v_fma_f32 v21, v24, v13, v114
	v_fma_f32 v22, v26, v14, v130
	v_fma_f32 v23, v26, v15, v146
	v_fma_f32 v16, -v25, v13, v20
	v_fma_f32 v17, v25, v12, v21
	v_fma_f32 v18, -v27, v15, v22
	v_fma_f32 v19, v27, v14, v23
	v_fma_f32 v20, v24, v16, v99
	v_fma_f32 v21, v24, v17, v115
	v_fma_f32 v22, v26, v18, v131
	v_fma_f32 v23, v26, v19, v147
	v_fma_f32 v12, -v25, v17, v20
	v_fma_f32 v13, v25, v16, v21
	v_fma_f32 v14, -v27, v19, v22
	v_fma_f32 v15, v27, v18, v23
	v_cvt_pk_f16_f32 v179, v16, v12
	v_cvt_pk_f16_f32 v183, v17, v13
	v_cvt_pk_f16_f32 v187, v18, v14
	v_cvt_pk_f16_f32 v191, v19, v15
	ds_write_b128 v93, v[32:35] offset:0
	ds_read_b64_tr_b16 v[194:195], v85 offset:2048
	ds_read_b64_tr_b16 v[196:197], v85 offset:2112
	ds_read_b64_tr_b16 v[198:199], v85 offset:2560
	ds_read_b64_tr_b16 v[200:201], v85 offset:2624
	ds_read_b64_tr_b16 v[206:207], v85 offset:3072
	ds_read_b64_tr_b16 v[208:209], v85 offset:3136
	ds_read_b64_tr_b16 v[210:211], v85 offset:3584
	ds_read_b64_tr_b16 v[212:213], v85 offset:3648
	v_fma_f32 v20, v24, v12, v100
	v_fma_f32 v21, v24, v13, v116
	v_fma_f32 v22, v26, v14, v132
	v_fma_f32 v23, v26, v15, v148
	v_fma_f32 v16, -v25, v13, v20
	v_fma_f32 v17, v25, v12, v21
	v_fma_f32 v18, -v27, v15, v22
	v_fma_f32 v19, v27, v14, v23
	v_fma_f32 v20, v24, v16, v101
	v_fma_f32 v21, v24, v17, v117
	v_fma_f32 v22, v26, v18, v133
	v_fma_f32 v23, v26, v19, v149
	v_fma_f32 v12, -v25, v17, v20
	v_fma_f32 v13, v25, v16, v21
	v_fma_f32 v14, -v27, v19, v22
	v_fma_f32 v15, v27, v18, v23
	v_cvt_pk_f16_f32 v180, v16, v12
	v_cvt_pk_f16_f32 v184, v17, v13
	v_cvt_pk_f16_f32 v188, v18, v14
	v_cvt_pk_f16_f32 v192, v19, v15
	s_waitcnt lgkmcnt(6)
	v_mfma_f32_16x16x32_f16 v[32:35], v[160:163], v[194:197], 0
	s_waitcnt lgkmcnt(4)
	v_mfma_f32_16x16x32_f16 v[32:35], v[164:167], v[198:201], v[32:35]
	s_waitcnt lgkmcnt(2)
	v_mfma_f32_16x16x32_f16 v[32:35], v[168:171], v[206:209], v[32:35]
	s_waitcnt lgkmcnt(0)
	v_mfma_f32_16x16x32_f16 v[32:35], v[172:175], v[210:213], v[32:35]
	v_fma_f32 v20, v24, v12, v102
	v_fma_f32 v21, v24, v13, v118
	v_fma_f32 v22, v26, v14, v134
	v_fma_f32 v23, v26, v15, v150
	v_fma_f32 v16, -v25, v13, v20
	v_fma_f32 v17, v25, v12, v21
	v_fma_f32 v18, -v27, v15, v22
	v_fma_f32 v19, v27, v14, v23
	v_fma_f32 v20, v24, v16, v103
	v_fma_f32 v21, v24, v17, v119
	v_fma_f32 v22, v26, v18, v135
	v_fma_f32 v23, v26, v19, v151
	v_fma_f32 v12, -v25, v17, v20
	v_fma_f32 v13, v25, v16, v21
	v_fma_f32 v14, -v27, v19, v22
	v_fma_f32 v15, v27, v18, v23
	v_cvt_pk_f16_f32 v181, v16, v12
	v_cvt_pk_f16_f32 v185, v17, v13
	v_cvt_pk_f16_f32 v189, v18, v14
	v_cvt_pk_f16_f32 v193, v19, v15
	ds_write_b128 v84, v[178:181] offset:0
	ds_write_b128 v84, v[182:185] offset:512
	ds_write_b128 v84, v[186:189] offset:1024
	ds_write_b128 v84, v[190:193] offset:1536
	v_fma_f32 v20, v24, v12, v104
	v_fma_f32 v21, v24, v13, v120
	v_fma_f32 v22, v26, v14, v136
	v_fma_f32 v23, v26, v15, v152
	v_fma_f32 v16, -v25, v13, v20
	v_fma_f32 v17, v25, v12, v21
	v_fma_f32 v18, -v27, v15, v22
	v_fma_f32 v19, v27, v14, v23
	ds_write_b128 v93, v[32:35] offset:4096
	v_fma_f32 v20, v24, v16, v105
	v_fma_f32 v21, v24, v17, v121
	v_fma_f32 v22, v26, v18, v137
	v_fma_f32 v23, v26, v19, v153
	v_fma_f32 v12, -v25, v17, v20
	v_fma_f32 v13, v25, v16, v21
	v_fma_f32 v14, -v27, v19, v22
	v_fma_f32 v15, v27, v18, v23
	v_cvt_pk_f16_f32 v178, v16, v12
	v_cvt_pk_f16_f32 v182, v17, v13
	v_cvt_pk_f16_f32 v186, v18, v14
	v_cvt_pk_f16_f32 v190, v19, v15
	v_fma_f32 v20, v24, v12, v106
	v_fma_f32 v21, v24, v13, v122
	v_fma_f32 v22, v26, v14, v138
	v_fma_f32 v23, v26, v15, v154
	v_fma_f32 v16, -v25, v13, v20
	v_fma_f32 v17, v25, v12, v21
	v_fma_f32 v18, -v27, v15, v22
	v_fma_f32 v19, v27, v14, v23
	v_fma_f32 v20, v24, v16, v107
	v_fma_f32 v21, v24, v17, v123
	v_fma_f32 v22, v26, v18, v139
	v_fma_f32 v23, v26, v19, v155
	v_fma_f32 v12, -v25, v17, v20
	v_fma_f32 v13, v25, v16, v21
	v_fma_f32 v14, -v27, v19, v22
	v_fma_f32 v15, v27, v18, v23
	v_cvt_pk_f16_f32 v179, v16, v12
	v_cvt_pk_f16_f32 v183, v17, v13
	v_cvt_pk_f16_f32 v187, v18, v14
	v_cvt_pk_f16_f32 v191, v19, v15
	v_fma_f32 v20, v24, v12, v108
	v_fma_f32 v21, v24, v13, v124
	v_fma_f32 v22, v26, v14, v140
	v_fma_f32 v23, v26, v15, v156
	v_fma_f32 v16, -v25, v13, v20
	v_fma_f32 v17, v25, v12, v21
	v_fma_f32 v18, -v27, v15, v22
	v_fma_f32 v19, v27, v14, v23
	v_fma_f32 v20, v24, v16, v109
	v_fma_f32 v21, v24, v17, v125
	v_fma_f32 v22, v26, v18, v141
	v_fma_f32 v23, v26, v19, v157
	v_fma_f32 v12, -v25, v17, v20
	v_fma_f32 v13, v25, v16, v21
	v_fma_f32 v14, -v27, v19, v22
	v_fma_f32 v15, v27, v18, v23
	v_cvt_pk_f16_f32 v180, v16, v12
	v_cvt_pk_f16_f32 v184, v17, v13
	v_cvt_pk_f16_f32 v188, v18, v14
	v_cvt_pk_f16_f32 v192, v19, v15
	v_fma_f32 v20, v24, v12, v110
	v_fma_f32 v21, v24, v13, v126
	v_fma_f32 v22, v26, v14, v142
	v_fma_f32 v23, v26, v15, v158
	v_fma_f32 v16, -v25, v13, v20
	v_fma_f32 v17, v25, v12, v21
	v_fma_f32 v18, -v27, v15, v22
	v_fma_f32 v19, v27, v14, v23
	v_fma_f32 v20, v24, v16, v111
	v_fma_f32 v21, v24, v17, v127
	v_fma_f32 v22, v26, v18, v143
	v_fma_f32 v23, v26, v19, v159
	v_fma_f32 v12, -v25, v17, v20
	v_fma_f32 v13, v25, v16, v21
	v_fma_f32 v14, -v27, v19, v22
	v_fma_f32 v15, v27, v18, v23
	v_cvt_pk_f16_f32 v181, v16, v12
	v_cvt_pk_f16_f32 v185, v17, v13
	v_cvt_pk_f16_f32 v189, v18, v14
	v_cvt_pk_f16_f32 v193, v19, v15
	ds_write_b128 v84, v[178:181] offset:4160
	ds_write_b128 v84, v[182:185] offset:4672
	ds_write_b128 v84, v[186:189] offset:5184
	ds_write_b128 v84, v[190:193] offset:5696
	v_mfma_f32_32x32x16_f16 v[96:111], v[60:63], v[36:39], 0
	v_mfma_f32_32x32x16_f16 v[112:127], v[60:63], v[40:43], 0
	v_mfma_f32_32x32x16_f16 v[128:143], v[60:63], v[44:47], 0
	v_mfma_f32_32x32x16_f16 v[144:159], v[60:63], v[48:51], 0
	v_add_u32_e32 v93, s77, v87
	ds_read_b64_tr_b16 v[194:195], v85 offset:0
	ds_read_b64_tr_b16 v[196:197], v85 offset:64
	ds_read_b64_tr_b16 v[198:199], v85 offset:512
	ds_read_b64_tr_b16 v[200:201], v85 offset:576
	ds_read_b64_tr_b16 v[206:207], v85 offset:1024
	ds_read_b64_tr_b16 v[208:209], v85 offset:1088
	ds_read_b64_tr_b16 v[210:211], v85 offset:1536
	ds_read_b64_tr_b16 v[212:213], v85 offset:1600
	s_nop 3
	v_fma_f32 v20, v24, v12, v96
	v_fma_f32 v21, v24, v13, v112
	v_fma_f32 v22, v26, v14, v128
	v_fma_f32 v23, v26, v15, v144
	v_fma_f32 v16, -v25, v13, v20
	v_fma_f32 v17, v25, v12, v21
	v_fma_f32 v18, -v27, v15, v22
	v_fma_f32 v19, v27, v14, v23
	v_fma_f32 v20, v24, v16, v97
	v_fma_f32 v21, v24, v17, v113
	v_fma_f32 v22, v26, v18, v129
	v_fma_f32 v23, v26, v19, v145
	v_fma_f32 v12, -v25, v17, v20
	v_fma_f32 v13, v25, v16, v21
	v_fma_f32 v14, -v27, v19, v22
	v_fma_f32 v15, v27, v18, v23
	v_cvt_pk_f16_f32 v178, v16, v12
	v_cvt_pk_f16_f32 v182, v17, v13
	v_cvt_pk_f16_f32 v186, v18, v14
	v_cvt_pk_f16_f32 v190, v19, v15
	s_waitcnt lgkmcnt(6)
	v_mfma_f32_16x16x32_f16 v[32:35], v[160:163], v[194:197], 0
	s_waitcnt lgkmcnt(4)
	v_mfma_f32_16x16x32_f16 v[32:35], v[164:167], v[198:201], v[32:35]
	s_waitcnt lgkmcnt(2)
	v_mfma_f32_16x16x32_f16 v[32:35], v[168:171], v[206:209], v[32:35]
	s_waitcnt lgkmcnt(0)
	v_mfma_f32_16x16x32_f16 v[32:35], v[172:175], v[210:213], v[32:35]
	v_fma_f32 v20, v24, v12, v98
	v_fma_f32 v21, v24, v13, v114
	v_fma_f32 v22, v26, v14, v130
	v_fma_f32 v23, v26, v15, v146
	v_fma_f32 v16, -v25, v13, v20
	v_fma_f32 v17, v25, v12, v21
	v_fma_f32 v18, -v27, v15, v22
	v_fma_f32 v19, v27, v14, v23
	v_fma_f32 v20, v24, v16, v99
	v_fma_f32 v21, v24, v17, v115
	v_fma_f32 v22, v26, v18, v131
	v_fma_f32 v23, v26, v19, v147
	v_fma_f32 v12, -v25, v17, v20
	v_fma_f32 v13, v25, v16, v21
	v_fma_f32 v14, -v27, v19, v22
	v_fma_f32 v15, v27, v18, v23
	v_cvt_pk_f16_f32 v179, v16, v12
	v_cvt_pk_f16_f32 v183, v17, v13
	v_cvt_pk_f16_f32 v187, v18, v14
	v_cvt_pk_f16_f32 v191, v19, v15
	ds_write_b128 v93, v[32:35] offset:0
	ds_read_b64_tr_b16 v[194:195], v85 offset:2048
	ds_read_b64_tr_b16 v[196:197], v85 offset:2112
	ds_read_b64_tr_b16 v[198:199], v85 offset:2560
	ds_read_b64_tr_b16 v[200:201], v85 offset:2624
	ds_read_b64_tr_b16 v[206:207], v85 offset:3072
	ds_read_b64_tr_b16 v[208:209], v85 offset:3136
	ds_read_b64_tr_b16 v[210:211], v85 offset:3584
	ds_read_b64_tr_b16 v[212:213], v85 offset:3648
	v_fma_f32 v20, v24, v12, v100
	v_fma_f32 v21, v24, v13, v116
	v_fma_f32 v22, v26, v14, v132
	v_fma_f32 v23, v26, v15, v148
	v_fma_f32 v16, -v25, v13, v20
	v_fma_f32 v17, v25, v12, v21
	v_fma_f32 v18, -v27, v15, v22
	v_fma_f32 v19, v27, v14, v23
	v_fma_f32 v20, v24, v16, v101
	v_fma_f32 v21, v24, v17, v117
	v_fma_f32 v22, v26, v18, v133
	v_fma_f32 v23, v26, v19, v149
	v_fma_f32 v12, -v25, v17, v20
	v_fma_f32 v13, v25, v16, v21
	v_fma_f32 v14, -v27, v19, v22
	v_fma_f32 v15, v27, v18, v23
	v_cvt_pk_f16_f32 v180, v16, v12
	v_cvt_pk_f16_f32 v184, v17, v13
	v_cvt_pk_f16_f32 v188, v18, v14
	v_cvt_pk_f16_f32 v192, v19, v15
	s_waitcnt lgkmcnt(6)
	v_mfma_f32_16x16x32_f16 v[32:35], v[160:163], v[194:197], 0
	s_waitcnt lgkmcnt(4)
	v_mfma_f32_16x16x32_f16 v[32:35], v[164:167], v[198:201], v[32:35]
	s_waitcnt lgkmcnt(2)
	v_mfma_f32_16x16x32_f16 v[32:35], v[168:171], v[206:209], v[32:35]
	s_waitcnt lgkmcnt(0)
	v_mfma_f32_16x16x32_f16 v[32:35], v[172:175], v[210:213], v[32:35]
	v_fma_f32 v20, v24, v12, v102
	v_fma_f32 v21, v24, v13, v118
	v_fma_f32 v22, v26, v14, v134
	v_fma_f32 v23, v26, v15, v150
	v_fma_f32 v16, -v25, v13, v20
	v_fma_f32 v17, v25, v12, v21
	v_fma_f32 v18, -v27, v15, v22
	v_fma_f32 v19, v27, v14, v23
	v_fma_f32 v20, v24, v16, v103
	v_fma_f32 v21, v24, v17, v119
	v_fma_f32 v22, v26, v18, v135
	v_fma_f32 v23, v26, v19, v151
	v_fma_f32 v12, -v25, v17, v20
	v_fma_f32 v13, v25, v16, v21
	v_fma_f32 v14, -v27, v19, v22
	v_fma_f32 v15, v27, v18, v23
	v_cvt_pk_f16_f32 v181, v16, v12
	v_cvt_pk_f16_f32 v185, v17, v13
	v_cvt_pk_f16_f32 v189, v18, v14
	v_cvt_pk_f16_f32 v193, v19, v15
	ds_write_b128 v84, v[178:181] offset:0
	ds_write_b128 v84, v[182:185] offset:512
	ds_write_b128 v84, v[186:189] offset:1024
	ds_write_b128 v84, v[190:193] offset:1536
	v_fma_f32 v20, v24, v12, v104
	v_fma_f32 v21, v24, v13, v120
	v_fma_f32 v22, v26, v14, v136
	v_fma_f32 v23, v26, v15, v152
	v_fma_f32 v16, -v25, v13, v20
	v_fma_f32 v17, v25, v12, v21
	v_fma_f32 v18, -v27, v15, v22
	v_fma_f32 v19, v27, v14, v23
	ds_write_b128 v93, v[32:35] offset:4096
	v_fma_f32 v20, v24, v16, v105
	v_fma_f32 v21, v24, v17, v121
	v_fma_f32 v22, v26, v18, v137
	v_fma_f32 v23, v26, v19, v153
	v_fma_f32 v12, -v25, v17, v20
	v_fma_f32 v13, v25, v16, v21
	v_fma_f32 v14, -v27, v19, v22
	v_fma_f32 v15, v27, v18, v23
	v_cvt_pk_f16_f32 v178, v16, v12
	v_cvt_pk_f16_f32 v182, v17, v13
	v_cvt_pk_f16_f32 v186, v18, v14
	v_cvt_pk_f16_f32 v190, v19, v15
	v_fma_f32 v20, v24, v12, v106
	v_fma_f32 v21, v24, v13, v122
	v_fma_f32 v22, v26, v14, v138
	v_fma_f32 v23, v26, v15, v154
	v_fma_f32 v16, -v25, v13, v20
	v_fma_f32 v17, v25, v12, v21
	v_fma_f32 v18, -v27, v15, v22
	v_fma_f32 v19, v27, v14, v23
	v_fma_f32 v20, v24, v16, v107
	v_fma_f32 v21, v24, v17, v123
	v_fma_f32 v22, v26, v18, v139
	v_fma_f32 v23, v26, v19, v155
	v_fma_f32 v12, -v25, v17, v20
	v_fma_f32 v13, v25, v16, v21
	v_fma_f32 v14, -v27, v19, v22
	v_fma_f32 v15, v27, v18, v23
	v_cvt_pk_f16_f32 v179, v16, v12
	v_cvt_pk_f16_f32 v183, v17, v13
	v_cvt_pk_f16_f32 v187, v18, v14
	v_cvt_pk_f16_f32 v191, v19, v15
	v_fma_f32 v20, v24, v12, v108
	v_fma_f32 v21, v24, v13, v124
	v_fma_f32 v22, v26, v14, v140
	v_fma_f32 v23, v26, v15, v156
	v_fma_f32 v16, -v25, v13, v20
	v_fma_f32 v17, v25, v12, v21
	v_fma_f32 v18, -v27, v15, v22
	v_fma_f32 v19, v27, v14, v23
	v_fma_f32 v20, v24, v16, v109
	v_fma_f32 v21, v24, v17, v125
	v_fma_f32 v22, v26, v18, v141
	v_fma_f32 v23, v26, v19, v157
	v_fma_f32 v12, -v25, v17, v20
	v_fma_f32 v13, v25, v16, v21
	v_fma_f32 v14, -v27, v19, v22
	v_fma_f32 v15, v27, v18, v23
	v_cvt_pk_f16_f32 v180, v16, v12
	v_cvt_pk_f16_f32 v184, v17, v13
	v_cvt_pk_f16_f32 v188, v18, v14
	v_cvt_pk_f16_f32 v192, v19, v15
	v_fma_f32 v20, v24, v12, v110
	v_fma_f32 v21, v24, v13, v126
	v_fma_f32 v22, v26, v14, v142
	v_fma_f32 v23, v26, v15, v158
	v_fma_f32 v16, -v25, v13, v20
	v_fma_f32 v17, v25, v12, v21
	v_fma_f32 v18, -v27, v15, v22
	v_fma_f32 v19, v27, v14, v23
	v_fma_f32 v20, v24, v16, v111
	v_fma_f32 v21, v24, v17, v127
	v_fma_f32 v22, v26, v18, v143
	v_fma_f32 v23, v26, v19, v159
	v_fma_f32 v12, -v25, v17, v20
	v_fma_f32 v13, v25, v16, v21
	v_fma_f32 v14, -v27, v19, v22
	v_fma_f32 v15, v27, v18, v23
	v_cvt_pk_f16_f32 v181, v16, v12
	v_cvt_pk_f16_f32 v185, v17, v13
	v_cvt_pk_f16_f32 v189, v18, v14
	v_cvt_pk_f16_f32 v193, v19, v15
	ds_write_b128 v84, v[178:181] offset:4160
	ds_write_b128 v84, v[182:185] offset:4672
	ds_write_b128 v84, v[186:189] offset:5184
	ds_write_b128 v84, v[190:193] offset:5696
	v_mfma_f32_32x32x16_f16 v[96:111], v[64:67], v[36:39], 0
	v_mfma_f32_32x32x16_f16 v[112:127], v[64:67], v[40:43], 0
	v_mfma_f32_32x32x16_f16 v[128:143], v[64:67], v[44:47], 0
	v_mfma_f32_32x32x16_f16 v[144:159], v[64:67], v[48:51], 0
	v_add_u32_e32 v93, s78, v87
	ds_read_b64_tr_b16 v[194:195], v85 offset:0
	ds_read_b64_tr_b16 v[196:197], v85 offset:64
	ds_read_b64_tr_b16 v[198:199], v85 offset:512
	ds_read_b64_tr_b16 v[200:201], v85 offset:576
	ds_read_b64_tr_b16 v[206:207], v85 offset:1024
	ds_read_b64_tr_b16 v[208:209], v85 offset:1088
	ds_read_b64_tr_b16 v[210:211], v85 offset:1536
	ds_read_b64_tr_b16 v[212:213], v85 offset:1600
	s_nop 3
	v_fma_f32 v20, v24, v12, v96
	v_fma_f32 v21, v24, v13, v112
	v_fma_f32 v22, v26, v14, v128
	v_fma_f32 v23, v26, v15, v144
	v_fma_f32 v16, -v25, v13, v20
	v_fma_f32 v17, v25, v12, v21
	v_fma_f32 v18, -v27, v15, v22
	v_fma_f32 v19, v27, v14, v23
	v_fma_f32 v20, v24, v16, v97
	v_fma_f32 v21, v24, v17, v113
	v_fma_f32 v22, v26, v18, v129
	v_fma_f32 v23, v26, v19, v145
	v_fma_f32 v12, -v25, v17, v20
	v_fma_f32 v13, v25, v16, v21
	v_fma_f32 v14, -v27, v19, v22
	v_fma_f32 v15, v27, v18, v23
	v_cvt_pk_f16_f32 v178, v16, v12
	v_cvt_pk_f16_f32 v182, v17, v13
	v_cvt_pk_f16_f32 v186, v18, v14
	v_cvt_pk_f16_f32 v190, v19, v15
	s_waitcnt lgkmcnt(6)
	v_mfma_f32_16x16x32_f16 v[32:35], v[160:163], v[194:197], 0
	s_waitcnt lgkmcnt(4)
	v_mfma_f32_16x16x32_f16 v[32:35], v[164:167], v[198:201], v[32:35]
	s_waitcnt lgkmcnt(2)
	v_mfma_f32_16x16x32_f16 v[32:35], v[168:171], v[206:209], v[32:35]
	s_waitcnt lgkmcnt(0)
	v_mfma_f32_16x16x32_f16 v[32:35], v[172:175], v[210:213], v[32:35]
	v_fma_f32 v20, v24, v12, v98
	v_fma_f32 v21, v24, v13, v114
	v_fma_f32 v22, v26, v14, v130
	v_fma_f32 v23, v26, v15, v146
	v_fma_f32 v16, -v25, v13, v20
	v_fma_f32 v17, v25, v12, v21
	v_fma_f32 v18, -v27, v15, v22
	v_fma_f32 v19, v27, v14, v23
	v_fma_f32 v20, v24, v16, v99
	v_fma_f32 v21, v24, v17, v115
	v_fma_f32 v22, v26, v18, v131
	v_fma_f32 v23, v26, v19, v147
	v_fma_f32 v12, -v25, v17, v20
	v_fma_f32 v13, v25, v16, v21
	v_fma_f32 v14, -v27, v19, v22
	v_fma_f32 v15, v27, v18, v23
	v_cvt_pk_f16_f32 v179, v16, v12
	v_cvt_pk_f16_f32 v183, v17, v13
	v_cvt_pk_f16_f32 v187, v18, v14
	v_cvt_pk_f16_f32 v191, v19, v15
	ds_write_b128 v93, v[32:35] offset:0
	ds_read_b64_tr_b16 v[194:195], v85 offset:2048
	ds_read_b64_tr_b16 v[196:197], v85 offset:2112
	ds_read_b64_tr_b16 v[198:199], v85 offset:2560
	ds_read_b64_tr_b16 v[200:201], v85 offset:2624
	ds_read_b64_tr_b16 v[206:207], v85 offset:3072
	ds_read_b64_tr_b16 v[208:209], v85 offset:3136
	ds_read_b64_tr_b16 v[210:211], v85 offset:3584
	ds_read_b64_tr_b16 v[212:213], v85 offset:3648
	v_fma_f32 v20, v24, v12, v100
	v_fma_f32 v21, v24, v13, v116
	v_fma_f32 v22, v26, v14, v132
	v_fma_f32 v23, v26, v15, v148
	v_fma_f32 v16, -v25, v13, v20
	v_fma_f32 v17, v25, v12, v21
	v_fma_f32 v18, -v27, v15, v22
	v_fma_f32 v19, v27, v14, v23
	v_fma_f32 v20, v24, v16, v101
	v_fma_f32 v21, v24, v17, v117
	v_fma_f32 v22, v26, v18, v133
	v_fma_f32 v23, v26, v19, v149
	v_fma_f32 v12, -v25, v17, v20
	v_fma_f32 v13, v25, v16, v21
	v_fma_f32 v14, -v27, v19, v22
	v_fma_f32 v15, v27, v18, v23
	v_cvt_pk_f16_f32 v180, v16, v12
	v_cvt_pk_f16_f32 v184, v17, v13
	v_cvt_pk_f16_f32 v188, v18, v14
	v_cvt_pk_f16_f32 v192, v19, v15
	s_waitcnt lgkmcnt(6)
	v_mfma_f32_16x16x32_f16 v[32:35], v[160:163], v[194:197], 0
	s_waitcnt lgkmcnt(4)
	v_mfma_f32_16x16x32_f16 v[32:35], v[164:167], v[198:201], v[32:35]
	s_waitcnt lgkmcnt(2)
	v_mfma_f32_16x16x32_f16 v[32:35], v[168:171], v[206:209], v[32:35]
	s_waitcnt lgkmcnt(0)
	v_mfma_f32_16x16x32_f16 v[32:35], v[172:175], v[210:213], v[32:35]
	v_fma_f32 v20, v24, v12, v102
	v_fma_f32 v21, v24, v13, v118
	v_fma_f32 v22, v26, v14, v134
	v_fma_f32 v23, v26, v15, v150
	v_fma_f32 v16, -v25, v13, v20
	v_fma_f32 v17, v25, v12, v21
	v_fma_f32 v18, -v27, v15, v22
	v_fma_f32 v19, v27, v14, v23
	v_fma_f32 v20, v24, v16, v103
	v_fma_f32 v21, v24, v17, v119
	v_fma_f32 v22, v26, v18, v135
	v_fma_f32 v23, v26, v19, v151
	v_fma_f32 v12, -v25, v17, v20
	v_fma_f32 v13, v25, v16, v21
	v_fma_f32 v14, -v27, v19, v22
	v_fma_f32 v15, v27, v18, v23
	v_cvt_pk_f16_f32 v181, v16, v12
	v_cvt_pk_f16_f32 v185, v17, v13
	v_cvt_pk_f16_f32 v189, v18, v14
	v_cvt_pk_f16_f32 v193, v19, v15
	ds_write_b128 v84, v[178:181] offset:0
	ds_write_b128 v84, v[182:185] offset:512
	ds_write_b128 v84, v[186:189] offset:1024
	ds_write_b128 v84, v[190:193] offset:1536
	v_fma_f32 v20, v24, v12, v104
	v_fma_f32 v21, v24, v13, v120
	v_fma_f32 v22, v26, v14, v136
	v_fma_f32 v23, v26, v15, v152
	v_fma_f32 v16, -v25, v13, v20
	v_fma_f32 v17, v25, v12, v21
	v_fma_f32 v18, -v27, v15, v22
	v_fma_f32 v19, v27, v14, v23
	ds_write_b128 v93, v[32:35] offset:4096
	v_fma_f32 v20, v24, v16, v105
	v_fma_f32 v21, v24, v17, v121
	v_fma_f32 v22, v26, v18, v137
	v_fma_f32 v23, v26, v19, v153
	v_fma_f32 v12, -v25, v17, v20
	v_fma_f32 v13, v25, v16, v21
	v_fma_f32 v14, -v27, v19, v22
	v_fma_f32 v15, v27, v18, v23
	v_cvt_pk_f16_f32 v178, v16, v12
	v_cvt_pk_f16_f32 v182, v17, v13
	v_cvt_pk_f16_f32 v186, v18, v14
	v_cvt_pk_f16_f32 v190, v19, v15
	v_fma_f32 v20, v24, v12, v106
	v_fma_f32 v21, v24, v13, v122
	v_fma_f32 v22, v26, v14, v138
	v_fma_f32 v23, v26, v15, v154
	v_fma_f32 v16, -v25, v13, v20
	v_fma_f32 v17, v25, v12, v21
	v_fma_f32 v18, -v27, v15, v22
	v_fma_f32 v19, v27, v14, v23
	v_fma_f32 v20, v24, v16, v107
	v_fma_f32 v21, v24, v17, v123
	v_fma_f32 v22, v26, v18, v139
	v_fma_f32 v23, v26, v19, v155
	v_fma_f32 v12, -v25, v17, v20
	v_fma_f32 v13, v25, v16, v21
	v_fma_f32 v14, -v27, v19, v22
	v_fma_f32 v15, v27, v18, v23
	v_cvt_pk_f16_f32 v179, v16, v12
	v_cvt_pk_f16_f32 v183, v17, v13
	v_cvt_pk_f16_f32 v187, v18, v14
	v_cvt_pk_f16_f32 v191, v19, v15
	v_fma_f32 v20, v24, v12, v108
	v_fma_f32 v21, v24, v13, v124
	v_fma_f32 v22, v26, v14, v140
	v_fma_f32 v23, v26, v15, v156
	v_fma_f32 v16, -v25, v13, v20
	v_fma_f32 v17, v25, v12, v21
	v_fma_f32 v18, -v27, v15, v22
	v_fma_f32 v19, v27, v14, v23
	v_fma_f32 v20, v24, v16, v109
	v_fma_f32 v21, v24, v17, v125
	v_fma_f32 v22, v26, v18, v141
	v_fma_f32 v23, v26, v19, v157
	v_fma_f32 v12, -v25, v17, v20
	v_fma_f32 v13, v25, v16, v21
	v_fma_f32 v14, -v27, v19, v22
	v_fma_f32 v15, v27, v18, v23
	v_cvt_pk_f16_f32 v180, v16, v12
	v_cvt_pk_f16_f32 v184, v17, v13
	v_cvt_pk_f16_f32 v188, v18, v14
	v_cvt_pk_f16_f32 v192, v19, v15
	v_fma_f32 v20, v24, v12, v110
	v_fma_f32 v21, v24, v13, v126
	v_fma_f32 v22, v26, v14, v142
	v_fma_f32 v23, v26, v15, v158
	v_fma_f32 v16, -v25, v13, v20
	v_fma_f32 v17, v25, v12, v21
	v_fma_f32 v18, -v27, v15, v22
	v_fma_f32 v19, v27, v14, v23
	v_fma_f32 v20, v24, v16, v111
	v_fma_f32 v21, v24, v17, v127
	v_fma_f32 v22, v26, v18, v143
	v_fma_f32 v23, v26, v19, v159
	v_fma_f32 v12, -v25, v17, v20
	v_fma_f32 v13, v25, v16, v21
	v_fma_f32 v14, -v27, v19, v22
	v_fma_f32 v15, v27, v18, v23
	v_cvt_pk_f16_f32 v181, v16, v12
	v_cvt_pk_f16_f32 v185, v17, v13
	v_cvt_pk_f16_f32 v189, v18, v14
	v_cvt_pk_f16_f32 v193, v19, v15
	ds_write_b128 v84, v[178:181] offset:4160
	ds_write_b128 v84, v[182:185] offset:4672
	ds_write_b128 v84, v[186:189] offset:5184
	ds_write_b128 v84, v[190:193] offset:5696
	v_add_u32_e32 v93, s79, v87
	ds_read_b64_tr_b16 v[194:195], v85 offset:0
	ds_read_b64_tr_b16 v[196:197], v85 offset:64
	ds_read_b64_tr_b16 v[198:199], v85 offset:512
	ds_read_b64_tr_b16 v[200:201], v85 offset:576
	ds_read_b64_tr_b16 v[206:207], v85 offset:1024
	ds_read_b64_tr_b16 v[208:209], v85 offset:1088
	ds_read_b64_tr_b16 v[210:211], v85 offset:1536
	ds_read_b64_tr_b16 v[212:213], v85 offset:1600
	s_waitcnt lgkmcnt(6)
	v_mfma_f32_16x16x32_f16 v[32:35], v[160:163], v[194:197], 0
	s_waitcnt lgkmcnt(4)
	v_mfma_f32_16x16x32_f16 v[32:35], v[164:167], v[198:201], v[32:35]
	s_waitcnt lgkmcnt(2)
	v_mfma_f32_16x16x32_f16 v[32:35], v[168:171], v[206:209], v[32:35]
	s_waitcnt lgkmcnt(0)
	v_mfma_f32_16x16x32_f16 v[32:35], v[172:175], v[210:213], v[32:35]
	s_nop 7
	s_nop 1
	ds_write_b128 v93, v[32:35] offset:0
	ds_read_b64_tr_b16 v[194:195], v85 offset:2048
	ds_read_b64_tr_b16 v[196:197], v85 offset:2112
	ds_read_b64_tr_b16 v[198:199], v85 offset:2560
	ds_read_b64_tr_b16 v[200:201], v85 offset:2624
	ds_read_b64_tr_b16 v[206:207], v85 offset:3072
	ds_read_b64_tr_b16 v[208:209], v85 offset:3136
	ds_read_b64_tr_b16 v[210:211], v85 offset:3584
	ds_read_b64_tr_b16 v[212:213], v85 offset:3648
	s_waitcnt lgkmcnt(6)
	v_mfma_f32_16x16x32_f16 v[32:35], v[160:163], v[194:197], 0
	s_waitcnt lgkmcnt(4)
	v_mfma_f32_16x16x32_f16 v[32:35], v[164:167], v[198:201], v[32:35]
	s_waitcnt lgkmcnt(2)
	v_mfma_f32_16x16x32_f16 v[32:35], v[168:171], v[206:209], v[32:35]
	s_waitcnt lgkmcnt(0)
	v_mfma_f32_16x16x32_f16 v[32:35], v[172:175], v[210:213], v[32:35]
	s_nop 7
	s_nop 1
	ds_write_b128 v93, v[32:35] offset:4096
	s_waitcnt lgkmcnt(0)
	v_mov_b32_e32 v230, s85
	ds_write_b32 v202, v230
	s_mov_b32 vcc_lo, 0
